# ACT tile re-layout: each UP-epilogue store instruction writes one contiguous 1 KiB block (FIX stores and DOWN A-loader offsets remapped to match)
# speedup vs baseline: 1.0022x; 1.0022x over previous
;     __device__ __forceinline__ void operator()(f32x4 (&acc)[2][2][4][2], const pg8::Unit& u, int ui, int wr, int wc, int fr, int fq) const {
;         const int b = u.pm >> 4, lrow = wr * 128 + fr * 8, jc = u.pn * 128 + wc * 32 + fq * 8, swc = u.pn * 256 + wc * 32 + fq * 8;
;         {   f32x4 swa[2], swv[2];
; #pragma unroll
;             for (int n = 0; n < 2; ++n) { swa[n] = *(const f32x4*)(SW + (size_t)b * NUP + swc + n * 4); swv[n] = *(const f32x4*)(SW + (size_t)b * NUP + swc + 128 + n * 4); }
; #pragma unroll
;             for (int ai = 0; ai < 2; ++ai)
; #pragma unroll
;                 for (int m = 0; m < 4; ++m) { const float r = RSTD[ui * 256 + lrow + 4 * ai + m];
; #pragma unroll
;                     for (int n = 0; n < 2; ++n) { acc[ai][0][m][n] = acc[ai][0][m][n] * r + swa[n]; acc[ai][1][m][n] = acc[ai][1][m][n] * r + swv[n]; } }
;         }
;         {   const int kb = u.pm * 2 + wr;
;             if (fr == 0) { float* pa = HA + ((size_t)kb * 4) * DFF + jc; float* pv = HV + ((size_t)kb * 2) * DFF + jc;
;                 *(f32x4*)pa = acc[0][0][0][0]; *(f32x4*)(pa + 4) = acc[0][0][0][1]; *(f32x4*)(pa + DFF) = acc[0][0][1][0]; *(f32x4*)(pa + DFF + 4) = acc[0][0][1][1];
;                 *(f32x4*)pv = acc[0][1][0][0]; *(f32x4*)(pv + 4) = acc[0][1][0][1]; *(f32x4*)(pv + DFF) = acc[0][1][1][0]; *(f32x4*)(pv + DFF + 4) = acc[0][1][1][1]; }
;             if (fr == 15) { float* pa = HA + ((size_t)kb * 4 + 2) * DFF + jc;
;                 store_wt(pa, __builtin_bit_cast(u32x4, acc[1][0][2][0])); store_wt(pa + 4, __builtin_bit_cast(u32x4, acc[1][0][2][1])); store_wt(pa + DFF, __builtin_bit_cast(u32x4, acc[1][0][3][0])); store_wt(pa + DFF + 4, __builtin_bit_cast(u32x4, acc[1][0][3][1])); } }
; #pragma unroll
;         for (int n = 0; n < 2; ++n) {
;             const f32x4 cbv = *(const f32x4*)(cb + jc + n * 4), w0 = *(const f32x4*)(cw + jc + n * 4), w1 = *(const f32x4*)(cw + DFF + jc + n * 4), w2 = *(const f32x4*)(cw + 2 * DFF + jc + n * 4);
;             f32x4 p2, p1;
;             { const f32x4 x6 = acc[1][0][2][n], x7 = acc[1][0][3][n];
;               p2 = (f32x4){dpp_z<0x111>(x6.x), dpp_z<0x111>(x6.y), dpp_z<0x111>(x6.z), dpp_z<0x111>(x6.w)};
;               p1 = (f32x4){dpp_z<0x111>(x7.x), dpp_z<0x111>(x7.y), dpp_z<0x111>(x7.z), dpp_z<0x111>(x7.w)}; }
.LBB0_1265:
	s_or_b64 exec, exec, s[34:35]
	v_mov_b32_e32 v194, v148
	v_mov_b32_e32 v195, v148
	v_pk_fma_f32 v[116:117], v[94:95], v[156:157], v[138:139] op_sel_hi:[1,0,1]
	v_pk_fma_f32 v[94:95], v[108:109], v[156:157], v[144:145] op_sel_hi:[1,0,1]
	v_pk_fma_f32 v[108:109], v[90:91], v[156:157], v[134:135] op_sel_hi:[1,0,1]
	v_mov_b32_e32 v90, v157
	v_mov_b32_e32 v196, v149
	v_mov_b32_e32 v197, v149
	v_pk_fma_f32 v[184:185], v[112:113], v[156:157], v[152:153] op_sel_hi:[1,0,1]
	v_pk_fma_f32 v[186:187], v[110:111], v[156:157], v[150:151] op_sel_hi:[1,0,1]
	v_pk_fma_f32 v[114:115], v[96:97], v[156:157], v[140:141] op_sel_hi:[1,0,1]
	v_pk_fma_f32 v[96:97], v[106:107], v[156:157], v[142:143] op_sel_hi:[1,0,1]
	v_pk_fma_f32 v[106:107], v[92:93], v[156:157], v[136:137] op_sel_hi:[1,0,1]
	v_pk_fma_f32 v[190:191], v[86:87], v[90:91], v[138:139] op_sel_hi:[1,0,1]
	v_pk_fma_f32 v[86:87], v[100:101], v[90:91], v[144:145] op_sel_hi:[1,0,1]
	v_pk_fma_f32 v[100:101], v[82:83], v[90:91], v[134:135] op_sel_hi:[1,0,1]
	v_pk_fma_f32 v[156:157], v[80:81], v[146:147], v[152:153] op_sel_hi:[1,0,1]
	v_pk_fma_f32 v[80:81], v[76:77], v[146:147], v[144:145] op_sel_hi:[1,0,1]
	v_pk_fma_f32 v[82:83], v[50:51], v[146:147], v[134:135] op_sel:[0,1,0]
	v_mov_b32_e32 v50, v148
	v_mov_b32_e32 v51, v148
	v_pk_fma_f32 v[76:77], v[18:19], v[194:195], v[134:135]
	v_lshlrev_b64 v[18:19], 2, v[170:171]
	v_pk_fma_f32 v[176:177], v[104:105], v[90:91], v[152:153] op_sel_hi:[1,0,1]
	v_pk_fma_f32 v[154:155], v[78:79], v[146:147], v[150:151] op_sel_hi:[1,0,1]
	v_pk_fma_f32 v[180:181], v[62:63], v[146:147], v[138:139] op_sel_hi:[1,0,1]
	v_pk_fma_f32 v[78:79], v[74:75], v[146:147], v[142:143] op_sel_hi:[1,0,1]
	v_pk_fma_f32 v[152:153], v[72:73], v[146:147], v[152:153] op_sel:[0,1,0]
	v_pk_fma_f32 v[172:173], v[54:55], v[146:147], v[138:139] op_sel:[0,1,0]
	v_pk_fma_f32 v[72:73], v[68:69], v[146:147], v[144:145] op_sel:[0,1,0]
	v_pk_fma_f32 v[144:145], v[22:23], v[194:195], v[138:139]
	v_pk_fma_f32 v[74:75], v[20:21], v[50:51], v[136:137]
	v_mov_b32_e32 v148, v149
	v_pk_fma_f32 v[138:139], v[14:15], v[196:197], v[138:139]
	v_lshl_add_u64 v[14:15], s[16:17], 0, v[18:19]
	v_lshl_add_u64 v[20:21], s[14:15], 0, v[18:19]
	v_pk_fma_f32 v[178:179], v[102:103], v[90:91], v[150:151] op_sel_hi:[1,0,1]
	v_pk_fma_f32 v[188:189], v[88:89], v[90:91], v[140:141] op_sel_hi:[1,0,1]
	v_pk_fma_f32 v[88:89], v[98:99], v[90:91], v[142:143] op_sel_hi:[1,0,1]
	v_pk_fma_f32 v[98:99], v[84:85], v[90:91], v[136:137] op_sel_hi:[1,0,1]
	v_pk_fma_f32 v[182:183], v[64:65], v[146:147], v[140:141] op_sel_hi:[1,0,1]
	v_pk_fma_f32 v[150:151], v[70:71], v[146:147], v[150:151] op_sel:[0,1,0]
	v_pk_fma_f32 v[174:175], v[56:57], v[146:147], v[140:141] op_sel:[0,1,0]
	v_pk_fma_f32 v[70:71], v[66:67], v[146:147], v[142:143] op_sel:[0,1,0]
	v_pk_fma_f32 v[84:85], v[52:53], v[146:147], v[136:137] op_sel:[0,1,0]
	v_pk_fma_f32 v[142:143], v[24:25], v[50:51], v[140:141]
	v_pk_fma_f32 v[140:141], v[16:17], v[148:149], v[140:141]
	v_pk_fma_f32 v[66:67], v[12:13], v[148:149], v[136:137]
	v_pk_fma_f32 v[68:69], v[10:11], v[196:197], v[134:135]
	global_load_dwordx4 v[10:13], v[14:15], off offset:16
	global_load_dwordx4 v[50:53], v[14:15], off
	s_nop 0
	global_load_dwordx4 v[14:17], v[20:21], off offset:16
	global_load_dwordx4 v[54:57], v[20:21], off
	v_lshl_add_u64 v[20:21], s[20:21], 0, v[18:19]
	v_pk_fma_f32 v[90:91], v[58:59], v[146:147], v[134:135] op_sel_hi:[1,0,1]
	global_load_dwordx4 v[22:25], v[20:21], off offset:16
	global_load_dwordx4 v[62:65], v[20:21], off
	v_lshl_add_u64 v[58:59], s[22:23], 0, v[18:19]
	v_pk_fma_f32 v[92:93], v[60:61], v[146:147], v[136:137] op_sel_hi:[1,0,1]
	global_load_dwordx4 v[18:21], v[58:59], off offset:16
	s_nop 0
	global_load_dwordx4 v[58:61], v[58:59], off
	v_mov_b32_e32 v102, 0
	v_mov_b32_e32 v103, 0
	v_mov_b32_e32 v104, 0
	v_mov_b32_e32 v105, 0
	v_mov_b32_dpp v102, v42 row_shr:1 row_mask:0xf bank_mask:0xf
	v_mov_b32_dpp v103, v43 row_shr:1 row_mask:0xf bank_mask:0xf
	v_mov_b32_dpp v104, v44 row_shr:1 row_mask:0xf bank_mask:0xf
	v_mov_b32_dpp v105, v45 row_shr:1 row_mask:0xf bank_mask:0xf
	v_mov_b32_e32 v110, 0
	v_mov_b32_e32 v111, 0
	v_mov_b32_e32 v112, 0
	v_mov_b32_e32 v113, 0
	v_mov_b32_dpp v110, v38 row_shr:1 row_mask:0xf bank_mask:0xf
	v_mov_b32_dpp v111, v39 row_shr:1 row_mask:0xf bank_mask:0xf
	v_mov_b32_dpp v112, v40 row_shr:1 row_mask:0xf bank_mask:0xf
	v_mov_b32_dpp v113, v41 row_shr:1 row_mask:0xf bank_mask:0xf
	s_mul_hi_i32 s11, s10, 0x2c0000
	s_mul_i32 s10, s10, 0x2c0000
	s_add_u32 s10, s67, s10
	s_addc_u32 s11, s68, s11
	s_andn2_b64 vcc, exec, s[6:7]
	s_waitcnt vmcnt(4)
	v_pk_fma_f32 v[104:105], v[56:57], v[104:105], v[52:53]
	v_pk_fma_f32 v[102:103], v[54:55], v[102:103], v[50:51]
	s_waitcnt vmcnt(2)
	v_pk_fma_f32 v[104:105], v[64:65], v[112:113], v[104:105]
	v_pk_fma_f32 v[102:103], v[62:63], v[110:111], v[102:103]
	v_pk_fma_f32 v[112:113], v[56:57], v[112:113], v[52:53]
	s_waitcnt vmcnt(0)
; __device__ __forceinline__ f32x4 silu4(const f32x4 p) { f32x4 r; r.x = siluf(p.x); r.y = siluf(p.y); r.z = siluf(p.z); r.w = siluf(p.w); return r; }
; template <int CTRL> __device__ __forceinline__ float dpp_z(float v) { return __int_as_float(__builtin_amdgcn_update_dpp(0, __float_as_int(v), CTRL, 0xf, 0xf, false)); }
;     __device__ __forceinline__ void operator()(f32x4 (&acc)[2][2][4][2], const pg8::Unit& u, int ui, int wr, int wc, int fr, int fq) const {
;     ...
;         for (int n = 0; n < 2; ++n) {
;             const f32x4 cbv = *(const f32x4*)(cb + jc + n * 4), w0 = *(const f32x4*)(cw + jc + n * 4), w1 = *(const f32x4*)(cw + DFF + jc + n * 4), w2 = *(const f32x4*)(cw + 2 * DFF + jc + n * 4);
;             f32x4 p2, p1;
;             { const f32x4 x6 = acc[1][0][2][n], x7 = acc[1][0][3][n];
;               p2 = (f32x4){dpp_z<0x111>(x6.x), dpp_z<0x111>(x6.y), dpp_z<0x111>(x6.z), dpp_z<0x111>(x6.w)};
;               p1 = (f32x4){dpp_z<0x111>(x7.x), dpp_z<0x111>(x7.y), dpp_z<0x111>(x7.z), dpp_z<0x111>(x7.w)}; }
; #pragma unroll
;             for (int j = 0; j < 8; ++j) { const f32x4 x = acc[j >> 2][0][j & 3][n];
;                 const f32x4 cv = cbv + w0 * p2 + w1 * p1 + w2 * x;
;                 acc[j >> 2][1][j & 3][n] = silu4(cv) * acc[j >> 2][1][j & 3][n];
;                 p2 = p1; p1 = x; }
	v_pk_fma_f32 v[104:105], v[128:129], v[60:61], v[104:105]
	v_pk_fma_f32 v[102:103], v[126:127], v[58:59], v[102:103]
	v_mul_f32_e32 v136, 0xbfb8aa3b, v104
	v_mul_f32_e32 v134, 0xbfb8aa3b, v102
	v_mul_f32_e32 v135, 0xbfb8aa3b, v103
	v_mul_f32_e32 v137, 0xbfb8aa3b, v105
	v_exp_f32_e32 v134, v134
	v_exp_f32_e32 v135, v135
	v_exp_f32_e32 v136, v136
	v_exp_f32_e32 v137, v137
	v_add_f32_e32 v134, 1.0, v134
	v_add_f32_e32 v135, 1.0, v135
	v_add_f32_e32 v136, 1.0, v136
	v_add_f32_e32 v137, 1.0, v137
	v_rcp_f32_e32 v134, v134
	v_rcp_f32_e32 v135, v135
	v_rcp_f32_e32 v136, v136
	v_rcp_f32_e32 v137, v137
	v_pk_fma_f32 v[110:111], v[54:55], v[110:111], v[50:51]
	v_pk_fma_f32 v[112:113], v[128:129], v[64:65], v[112:113]
	v_pk_fma_f32 v[110:111], v[126:127], v[62:63], v[110:111]
	v_pk_mul_f32 v[104:105], v[104:105], v[136:137]
	v_pk_mul_f32 v[134:135], v[102:103], v[134:135]
	v_pk_fma_f32 v[112:113], v[120:121], v[60:61], v[112:113]
	v_pk_fma_f32 v[110:111], v[118:119], v[58:59], v[110:111]
	v_pk_mul_f32 v[102:103], v[132:133], v[104:105]
	v_pk_mul_f32 v[104:105], v[130:131], v[134:135]
	v_mul_f32_e32 v130, 0xbfb8aa3b, v110
	v_mul_f32_e32 v131, 0xbfb8aa3b, v111
	v_mul_f32_e32 v132, 0xbfb8aa3b, v112
	v_mul_f32_e32 v133, 0xbfb8aa3b, v113
	v_exp_f32_e32 v130, v130
	v_exp_f32_e32 v131, v131
	v_exp_f32_e32 v132, v132
	v_exp_f32_e32 v133, v133
	v_add_f32_e32 v130, 1.0, v130
	v_add_f32_e32 v131, 1.0, v131
	v_add_f32_e32 v132, 1.0, v132
	v_add_f32_e32 v133, 1.0, v133
	v_rcp_f32_e32 v130, v130
	v_rcp_f32_e32 v131, v131
	v_rcp_f32_e32 v132, v132
	v_rcp_f32_e32 v133, v133
	v_pk_mul_f32 v[130:131], v[110:111], v[130:131]
	v_pk_mul_f32 v[112:113], v[112:113], v[132:133]
	s_nop 0
	v_pk_mul_f32 v[110:111], v[124:125], v[112:113]
	v_pk_mul_f32 v[112:113], v[122:123], v[130:131]
	v_pk_fma_f32 v[122:123], v[128:129], v[56:57], v[52:53]
	v_pk_fma_f32 v[124:125], v[126:127], v[54:55], v[50:51]
	v_pk_fma_f32 v[122:123], v[120:121], v[64:65], v[122:123]
	v_pk_fma_f32 v[124:125], v[118:119], v[62:63], v[124:125]
	v_pk_fma_f32 v[122:123], v[184:185], v[60:61], v[122:123]
	v_pk_fma_f32 v[124:125], v[186:187], v[58:59], v[124:125]
	v_mul_f32_e32 v128, 0xbfb8aa3b, v122
	v_mul_f32_e32 v126, 0xbfb8aa3b, v124
	v_mul_f32_e32 v127, 0xbfb8aa3b, v125
	v_mul_f32_e32 v129, 0xbfb8aa3b, v123
	v_exp_f32_e32 v126, v126
	v_exp_f32_e32 v127, v127
	v_exp_f32_e32 v128, v128
	v_exp_f32_e32 v129, v129
	v_add_f32_e32 v126, 1.0, v126
	v_add_f32_e32 v127, 1.0, v127
	v_add_f32_e32 v128, 1.0, v128
	v_add_f32_e32 v129, 1.0, v129
	v_rcp_f32_e32 v126, v126
	v_rcp_f32_e32 v127, v127
	v_rcp_f32_e32 v128, v128
	v_rcp_f32_e32 v129, v129
	v_pk_fma_f32 v[120:121], v[120:121], v[56:57], v[52:53]
	v_pk_fma_f32 v[118:119], v[118:119], v[54:55], v[50:51]
	v_pk_fma_f32 v[120:121], v[184:185], v[64:65], v[120:121]
	v_pk_fma_f32 v[118:119], v[186:187], v[62:63], v[118:119]
	v_pk_mul_f32 v[122:123], v[122:123], v[128:129]
	v_pk_mul_f32 v[124:125], v[124:125], v[126:127]
	v_pk_fma_f32 v[120:121], v[176:177], v[60:61], v[120:121]
	v_pk_fma_f32 v[118:119], v[178:179], v[58:59], v[118:119]
	v_pk_mul_f32 v[114:115], v[114:115], v[122:123]
	v_pk_mul_f32 v[116:117], v[116:117], v[124:125]
	v_mul_f32_e32 v122, 0xbfb8aa3b, v118
	v_mul_f32_e32 v123, 0xbfb8aa3b, v119
	v_mul_f32_e32 v124, 0xbfb8aa3b, v120
	v_mul_f32_e32 v125, 0xbfb8aa3b, v121
	v_exp_f32_e32 v122, v122
	v_exp_f32_e32 v123, v123
	v_exp_f32_e32 v124, v124
	v_exp_f32_e32 v125, v125
	v_add_f32_e32 v122, 1.0, v122
	v_add_f32_e32 v123, 1.0, v123
	v_add_f32_e32 v124, 1.0, v124
	v_add_f32_e32 v125, 1.0, v125
	v_rcp_f32_e32 v122, v122
	v_rcp_f32_e32 v123, v123
	v_rcp_f32_e32 v124, v124
	v_rcp_f32_e32 v125, v125
	v_pk_mul_f32 v[122:123], v[118:119], v[122:123]
	v_pk_mul_f32 v[120:121], v[120:121], v[124:125]
	s_nop 0
	v_pk_mul_f32 v[118:119], v[188:189], v[120:121]
	v_pk_mul_f32 v[120:121], v[190:191], v[122:123]
	v_pk_fma_f32 v[122:123], v[186:187], v[54:55], v[50:51]
	v_pk_fma_f32 v[124:125], v[184:185], v[56:57], v[52:53]
	v_pk_fma_f32 v[122:123], v[178:179], v[62:63], v[122:123]
	v_pk_fma_f32 v[124:125], v[176:177], v[64:65], v[124:125]
	v_pk_fma_f32 v[122:123], v[154:155], v[58:59], v[122:123]
	v_pk_fma_f32 v[124:125], v[156:157], v[60:61], v[124:125]
	v_mul_f32_e32 v126, 0xbfb8aa3b, v122
	v_mul_f32_e32 v127, 0xbfb8aa3b, v123
	v_mul_f32_e32 v128, 0xbfb8aa3b, v124
	v_mul_f32_e32 v129, 0xbfb8aa3b, v125
	v_exp_f32_e32 v126, v126
	v_exp_f32_e32 v127, v127
	v_exp_f32_e32 v128, v128
	v_exp_f32_e32 v129, v129
	v_add_f32_e32 v126, 1.0, v126
	v_add_f32_e32 v127, 1.0, v127
	v_add_f32_e32 v128, 1.0, v128
	v_add_f32_e32 v129, 1.0, v129
	v_rcp_f32_e32 v126, v126
	v_rcp_f32_e32 v127, v127
	v_rcp_f32_e32 v128, v128
	v_rcp_f32_e32 v129, v129
	v_pk_mul_f32 v[126:127], v[122:123], v[126:127]
	v_pk_mul_f32 v[124:125], v[124:125], v[128:129]
	s_nop 0
	v_pk_mul_f32 v[122:123], v[182:183], v[124:125]
	v_pk_mul_f32 v[124:125], v[180:181], v[126:127]
	v_pk_fma_f32 v[126:127], v[176:177], v[56:57], v[52:53]
	v_pk_fma_f32 v[128:129], v[178:179], v[54:55], v[50:51]
	v_pk_fma_f32 v[126:127], v[156:157], v[64:65], v[126:127]
	v_pk_fma_f32 v[128:129], v[154:155], v[62:63], v[128:129]
	v_pk_fma_f32 v[126:127], v[152:153], v[60:61], v[126:127]
	v_pk_fma_f32 v[128:129], v[150:151], v[58:59], v[128:129]
	v_mul_f32_e32 v132, 0xbfb8aa3b, v126
	v_mul_f32_e32 v130, 0xbfb8aa3b, v128
	v_mul_f32_e32 v131, 0xbfb8aa3b, v129
	v_mul_f32_e32 v133, 0xbfb8aa3b, v127
	v_exp_f32_e32 v130, v130
	v_exp_f32_e32 v131, v131
	v_exp_f32_e32 v132, v132
	v_exp_f32_e32 v133, v133
	v_add_f32_e32 v130, 1.0, v130
	v_add_f32_e32 v131, 1.0, v131
	v_add_f32_e32 v132, 1.0, v132
	v_add_f32_e32 v133, 1.0, v133
	v_rcp_f32_e32 v130, v130
; __device__ __forceinline__ f32x4 silu4(const f32x4 p) { f32x4 r; r.x = siluf(p.x); r.y = siluf(p.y); r.z = siluf(p.z); r.w = siluf(p.w); return r; }
; template <int CTRL> __device__ __forceinline__ float dpp_z(float v) { return __int_as_float(__builtin_amdgcn_update_dpp(0, __float_as_int(v), CTRL, 0xf, 0xf, false)); }
;     __device__ __forceinline__ void operator()(f32x4 (&acc)[2][2][4][2], const pg8::Unit& u, int ui, int wr, int wc, int fr, int fq) const {
;     ...
;         for (int n = 0; n < 2; ++n) {
;             const f32x4 cbv = *(const f32x4*)(cb + jc + n * 4), w0 = *(const f32x4*)(cw + jc + n * 4), w1 = *(const f32x4*)(cw + DFF + jc + n * 4), w2 = *(const f32x4*)(cw + 2 * DFF + jc + n * 4);
;             f32x4 p2, p1;
;             { const f32x4 x6 = acc[1][0][2][n], x7 = acc[1][0][3][n];
;               p2 = (f32x4){dpp_z<0x111>(x6.x), dpp_z<0x111>(x6.y), dpp_z<0x111>(x6.z), dpp_z<0x111>(x6.w)};
;               p1 = (f32x4){dpp_z<0x111>(x7.x), dpp_z<0x111>(x7.y), dpp_z<0x111>(x7.z), dpp_z<0x111>(x7.w)}; }
; #pragma unroll
;             for (int j = 0; j < 8; ++j) { const f32x4 x = acc[j >> 2][0][j & 3][n];
;                 const f32x4 cv = cbv + w0 * p2 + w1 * p1 + w2 * x;
;                 acc[j >> 2][1][j & 3][n] = silu4(cv) * acc[j >> 2][1][j & 3][n];
;                 p2 = p1; p1 = x; }
	v_rcp_f32_e32 v131, v131
	v_rcp_f32_e32 v132, v132
	v_rcp_f32_e32 v133, v133
	v_pk_mul_f32 v[128:129], v[128:129], v[130:131]
	v_pk_fma_f32 v[130:131], v[156:157], v[56:57], v[52:53]
	v_pk_mul_f32 v[126:127], v[126:127], v[132:133]
	v_pk_fma_f32 v[132:133], v[154:155], v[54:55], v[50:51]
	v_pk_fma_f32 v[130:131], v[152:153], v[64:65], v[130:131]
	v_pk_fma_f32 v[132:133], v[150:151], v[62:63], v[132:133]
	v_pk_fma_f32 v[52:53], v[152:153], v[56:57], v[52:53]
	v_pk_fma_f32 v[50:51], v[150:151], v[54:55], v[50:51]
	v_pk_fma_f32 v[130:131], v[44:45], v[60:61], v[130:131]
	v_pk_fma_f32 v[132:133], v[42:43], v[58:59], v[132:133]
	v_pk_fma_f32 v[44:45], v[44:45], v[64:65], v[52:53]
	v_pk_fma_f32 v[42:43], v[42:43], v[62:63], v[50:51]
	v_pk_fma_f32 v[40:41], v[40:41], v[60:61], v[44:45]
	v_pk_fma_f32 v[38:39], v[38:39], v[58:59], v[42:43]
	v_mul_f32_e32 v44, 0xbfb8aa3b, v40
	v_mul_f32_e32 v42, 0xbfb8aa3b, v38
	v_mul_f32_e32 v43, 0xbfb8aa3b, v39
	v_mul_f32_e32 v45, 0xbfb8aa3b, v41
	v_exp_f32_e32 v42, v42
	v_exp_f32_e32 v43, v43
	v_exp_f32_e32 v44, v44
	v_exp_f32_e32 v45, v45
	v_add_f32_e32 v42, 1.0, v42
	v_add_f32_e32 v43, 1.0, v43
	v_add_f32_e32 v44, 1.0, v44
	v_add_f32_e32 v45, 1.0, v45
	v_rcp_f32_e32 v42, v42
	v_rcp_f32_e32 v43, v43
	v_rcp_f32_e32 v44, v44
	v_rcp_f32_e32 v45, v45
	v_mov_b32_e32 v50, 0
	v_pk_mul_f32 v[42:43], v[38:39], v[42:43]
	v_mov_b32_e32 v51, 0
	v_pk_mul_f32 v[40:41], v[40:41], v[44:45]
	v_mov_b32_e32 v44, 0
	v_pk_mul_f32 v[38:39], v[140:141], v[40:41]
	v_pk_mul_f32 v[40:41], v[138:139], v[42:43]
	v_mov_b32_e32 v42, 0
	v_mov_b32_e32 v43, 0
	v_mov_b32_e32 v45, 0
	v_mov_b32_dpp v42, v6 row_shr:1 row_mask:0xf bank_mask:0xf
	v_mov_b32_dpp v43, v7 row_shr:1 row_mask:0xf bank_mask:0xf
	v_mov_b32_dpp v44, v8 row_shr:1 row_mask:0xf bank_mask:0xf
	v_mov_b32_dpp v45, v9 row_shr:1 row_mask:0xf bank_mask:0xf
	v_mov_b32_e32 v52, 0
	v_mov_b32_e32 v53, 0
	v_mov_b32_dpp v50, v2 row_shr:1 row_mask:0xf bank_mask:0xf
	v_mov_b32_dpp v51, v3 row_shr:1 row_mask:0xf bank_mask:0xf
	v_mov_b32_dpp v52, v4 row_shr:1 row_mask:0xf bank_mask:0xf
	v_mov_b32_dpp v53, v5 row_shr:1 row_mask:0xf bank_mask:0xf
	v_pk_fma_f32 v[44:45], v[16:17], v[44:45], v[12:13]
	v_pk_fma_f32 v[42:43], v[14:15], v[42:43], v[10:11]
	v_pk_fma_f32 v[44:45], v[24:25], v[52:53], v[44:45]
	v_pk_fma_f32 v[42:43], v[22:23], v[50:51], v[42:43]
	v_pk_fma_f32 v[44:45], v[32:33], v[20:21], v[44:45]
	v_pk_fma_f32 v[42:43], v[30:31], v[18:19], v[42:43]
	v_mul_f32_e32 v56, 0xbfb8aa3b, v44
	v_mul_f32_e32 v54, 0xbfb8aa3b, v42
	v_mul_f32_e32 v55, 0xbfb8aa3b, v43
	v_mul_f32_e32 v57, 0xbfb8aa3b, v45
	v_exp_f32_e32 v54, v54
	v_exp_f32_e32 v55, v55
	v_exp_f32_e32 v56, v56
	v_exp_f32_e32 v57, v57
	v_add_f32_e32 v54, 1.0, v54
	v_add_f32_e32 v55, 1.0, v55
	v_add_f32_e32 v56, 1.0, v56
	v_add_f32_e32 v57, 1.0, v57
	v_rcp_f32_e32 v54, v54
	v_rcp_f32_e32 v55, v55
	v_rcp_f32_e32 v56, v56
	v_rcp_f32_e32 v57, v57
	v_mul_f32_e32 v134, 0xbfb8aa3b, v132
	v_pk_mul_f32 v[54:55], v[42:43], v[54:55]
	v_mul_f32_e32 v135, 0xbfb8aa3b, v133
	v_pk_mul_f32 v[44:45], v[44:45], v[56:57]
	v_mul_f32_e32 v136, 0xbfb8aa3b, v130
	v_pk_mul_f32 v[42:43], v[48:49], v[44:45]
	v_pk_mul_f32 v[44:45], v[46:47], v[54:55]
	v_pk_fma_f32 v[46:47], v[16:17], v[52:53], v[12:13]
	v_pk_fma_f32 v[48:49], v[14:15], v[50:51], v[10:11]
	v_pk_fma_f32 v[46:47], v[32:33], v[24:25], v[46:47]
	v_pk_fma_f32 v[48:49], v[30:31], v[22:23], v[48:49]
	v_pk_fma_f32 v[46:47], v[28:29], v[20:21], v[46:47]
	v_pk_fma_f32 v[48:49], v[26:27], v[18:19], v[48:49]
	v_mul_f32_e32 v52, 0xbfb8aa3b, v46
	v_mul_f32_e32 v50, 0xbfb8aa3b, v48
	v_mul_f32_e32 v51, 0xbfb8aa3b, v49
	v_mul_f32_e32 v53, 0xbfb8aa3b, v47
	v_exp_f32_e32 v50, v50
	v_exp_f32_e32 v51, v51
	v_exp_f32_e32 v52, v52
	v_exp_f32_e32 v53, v53
	v_add_f32_e32 v50, 1.0, v50
	v_add_f32_e32 v51, 1.0, v51
	v_add_f32_e32 v52, 1.0, v52
	v_add_f32_e32 v53, 1.0, v53
	v_rcp_f32_e32 v50, v50
	v_rcp_f32_e32 v51, v51
	v_rcp_f32_e32 v52, v52
	v_rcp_f32_e32 v53, v53
	v_pk_fma_f32 v[32:33], v[32:33], v[16:17], v[12:13]
	v_pk_fma_f32 v[30:31], v[30:31], v[14:15], v[10:11]
	v_pk_fma_f32 v[32:33], v[28:29], v[24:25], v[32:33]
	v_pk_fma_f32 v[30:31], v[26:27], v[22:23], v[30:31]
	v_pk_mul_f32 v[46:47], v[46:47], v[52:53]
	v_pk_mul_f32 v[48:49], v[48:49], v[50:51]
	v_pk_fma_f32 v[32:33], v[94:95], v[20:21], v[32:33]
	v_pk_fma_f32 v[30:31], v[96:97], v[18:19], v[30:31]
	v_pk_mul_f32 v[36:37], v[36:37], v[46:47]
	v_pk_mul_f32 v[34:35], v[34:35], v[48:49]
	v_mul_f32_e32 v46, 0xbfb8aa3b, v30
	v_mul_f32_e32 v47, 0xbfb8aa3b, v31
	v_mul_f32_e32 v48, 0xbfb8aa3b, v32
	v_mul_f32_e32 v49, 0xbfb8aa3b, v33
	v_exp_f32_e32 v46, v46
	v_exp_f32_e32 v47, v47
	v_exp_f32_e32 v48, v48
	v_exp_f32_e32 v49, v49
	v_add_f32_e32 v46, 1.0, v46
	v_add_f32_e32 v47, 1.0, v47
	v_add_f32_e32 v48, 1.0, v48
	v_add_f32_e32 v49, 1.0, v49
	v_rcp_f32_e32 v46, v46
	v_rcp_f32_e32 v47, v47
	v_rcp_f32_e32 v48, v48
	v_rcp_f32_e32 v49, v49
	v_pk_fma_f32 v[28:29], v[28:29], v[16:17], v[12:13]
	v_pk_fma_f32 v[26:27], v[26:27], v[14:15], v[10:11]
	v_pk_fma_f32 v[28:29], v[94:95], v[24:25], v[28:29]
	v_pk_fma_f32 v[26:27], v[96:97], v[22:23], v[26:27]
	v_pk_mul_f32 v[32:33], v[32:33], v[48:49]
	v_pk_mul_f32 v[46:47], v[30:31], v[46:47]
	v_pk_fma_f32 v[28:29], v[86:87], v[20:21], v[28:29]
	v_pk_fma_f32 v[26:27], v[88:89], v[18:19], v[26:27]
	v_pk_mul_f32 v[30:31], v[106:107], v[32:33]
	v_pk_mul_f32 v[32:33], v[108:109], v[46:47]
	v_mul_f32_e32 v46, 0xbfb8aa3b, v26
	v_mul_f32_e32 v47, 0xbfb8aa3b, v27
	v_mul_f32_e32 v48, 0xbfb8aa3b, v28
	v_mul_f32_e32 v49, 0xbfb8aa3b, v29
	v_exp_f32_e32 v46, v46
	v_exp_f32_e32 v47, v47
	v_exp_f32_e32 v48, v48
	v_exp_f32_e32 v49, v49
; __device__ __forceinline__ u32x4 pack8(const f32x4 a, const f32x4 b) { u32x4 w; w.x = cvt_pk_bf16(a.x, a.y); w.y = cvt_pk_bf16(a.z, a.w); w.z = cvt_pk_bf16(b.x, b.y); w.w = cvt_pk_bf16(b.z, b.w); return w; }
; __device__ __forceinline__ f32x4 silu4(const f32x4 p) { f32x4 r; r.x = siluf(p.x); r.y = siluf(p.y); r.z = siluf(p.z); r.w = siluf(p.w); return r; }
; template <int CTRL> __device__ __forceinline__ float dpp_z(float v) { return __int_as_float(__builtin_amdgcn_update_dpp(0, __float_as_int(v), CTRL, 0xf, 0xf, false)); }
;     __device__ __forceinline__ void operator()(f32x4 (&acc)[2][2][4][2], const pg8::Unit& u, int ui, int wr, int wc, int fr, int fq) const {
;     ...
;         for (int n = 0; n < 2; ++n) {
;             const f32x4 cbv = *(const f32x4*)(cb + jc + n * 4), w0 = *(const f32x4*)(cw + jc + n * 4), w1 = *(const f32x4*)(cw + DFF + jc + n * 4), w2 = *(const f32x4*)(cw + 2 * DFF + jc + n * 4);
;             f32x4 p2, p1;
;             { const f32x4 x6 = acc[1][0][2][n], x7 = acc[1][0][3][n];
;               p2 = (f32x4){dpp_z<0x111>(x6.x), dpp_z<0x111>(x6.y), dpp_z<0x111>(x6.z), dpp_z<0x111>(x6.w)};
;               p1 = (f32x4){dpp_z<0x111>(x7.x), dpp_z<0x111>(x7.y), dpp_z<0x111>(x7.z), dpp_z<0x111>(x7.w)}; }
; #pragma unroll
;             for (int j = 0; j < 8; ++j) { const f32x4 x = acc[j >> 2][0][j & 3][n];
;                 const f32x4 cv = cbv + w0 * p2 + w1 * p1 + w2 * x;
;                 acc[j >> 2][1][j & 3][n] = silu4(cv) * acc[j >> 2][1][j & 3][n];
;                 p2 = p1; p1 = x; }
;         }
; #pragma unroll
;         for (int j = 0; j < 8; ++j) *(u32x4*)(ACT + (size_t)u.pm * (256 * DFF) + (size_t)(jc >> 6) * (256 * 64) + (lrow + j) * 64 + (jc & 63)) = pack8(acc[j >> 2][1][j & 3][0], acc[j >> 2][1][j & 3][1]);
	v_add_f32_e32 v46, 1.0, v46
	v_add_f32_e32 v47, 1.0, v47
	v_add_f32_e32 v48, 1.0, v48
	v_add_f32_e32 v49, 1.0, v49
	v_rcp_f32_e32 v46, v46
	v_rcp_f32_e32 v47, v47
	v_rcp_f32_e32 v48, v48
	v_rcp_f32_e32 v49, v49
	v_mul_f32_e32 v137, 0xbfb8aa3b, v131
	v_pk_mul_f32 v[46:47], v[26:27], v[46:47]
	v_exp_f32_e32 v134, v134
	v_pk_mul_f32 v[28:29], v[28:29], v[48:49]
	v_pk_fma_f32 v[48:49], v[94:95], v[16:17], v[12:13]
	v_pk_mul_f32 v[26:27], v[98:99], v[28:29]
	v_pk_mul_f32 v[28:29], v[100:101], v[46:47]
	v_pk_fma_f32 v[46:47], v[96:97], v[14:15], v[10:11]
	v_pk_fma_f32 v[48:49], v[86:87], v[24:25], v[48:49]
	v_pk_fma_f32 v[46:47], v[88:89], v[22:23], v[46:47]
	v_pk_fma_f32 v[48:49], v[80:81], v[20:21], v[48:49]
	v_pk_fma_f32 v[46:47], v[78:79], v[18:19], v[46:47]
	v_mul_f32_e32 v52, 0xbfb8aa3b, v48
	v_mul_f32_e32 v50, 0xbfb8aa3b, v46
	v_mul_f32_e32 v51, 0xbfb8aa3b, v47
	v_mul_f32_e32 v53, 0xbfb8aa3b, v49
	v_exp_f32_e32 v50, v50
	v_exp_f32_e32 v51, v51
	v_exp_f32_e32 v52, v52
	v_exp_f32_e32 v53, v53
	v_add_f32_e32 v50, 1.0, v50
	v_add_f32_e32 v51, 1.0, v51
	v_add_f32_e32 v52, 1.0, v52
	v_add_f32_e32 v53, 1.0, v53
	v_rcp_f32_e32 v50, v50
	v_rcp_f32_e32 v51, v51
	v_rcp_f32_e32 v52, v52
	v_rcp_f32_e32 v53, v53
	v_exp_f32_e32 v135, v135
	v_pk_mul_f32 v[50:51], v[46:47], v[50:51]
	v_exp_f32_e32 v136, v136
	v_pk_mul_f32 v[48:49], v[48:49], v[52:53]
	v_pk_fma_f32 v[52:53], v[88:89], v[14:15], v[10:11]
	v_pk_mul_f32 v[46:47], v[92:93], v[48:49]
	v_pk_mul_f32 v[48:49], v[90:91], v[50:51]
	v_pk_fma_f32 v[50:51], v[86:87], v[16:17], v[12:13]
	v_pk_fma_f32 v[52:53], v[78:79], v[22:23], v[52:53]
	v_pk_fma_f32 v[50:51], v[80:81], v[24:25], v[50:51]
	v_pk_fma_f32 v[52:53], v[70:71], v[18:19], v[52:53]
	v_pk_fma_f32 v[50:51], v[72:73], v[20:21], v[50:51]
	v_mul_f32_e32 v54, 0xbfb8aa3b, v52
	v_mul_f32_e32 v56, 0xbfb8aa3b, v50
	v_mul_f32_e32 v57, 0xbfb8aa3b, v51
	v_mul_f32_e32 v55, 0xbfb8aa3b, v53
	v_exp_f32_e32 v56, v56
	v_exp_f32_e32 v57, v57
	v_exp_f32_e32 v54, v54
	v_exp_f32_e32 v55, v55
	v_add_f32_e32 v56, 1.0, v56
	v_add_f32_e32 v57, 1.0, v57
	v_add_f32_e32 v54, 1.0, v54
	v_add_f32_e32 v55, 1.0, v55
	v_rcp_f32_e32 v56, v56
	v_rcp_f32_e32 v57, v57
	v_rcp_f32_e32 v54, v54
	v_rcp_f32_e32 v55, v55
	v_exp_f32_e32 v137, v137
	v_pk_mul_f32 v[50:51], v[50:51], v[56:57]
	v_pk_fma_f32 v[56:57], v[78:79], v[14:15], v[10:11]
	v_pk_mul_f32 v[52:53], v[52:53], v[54:55]
	v_pk_fma_f32 v[54:55], v[80:81], v[16:17], v[12:13]
	v_pk_fma_f32 v[56:57], v[70:71], v[22:23], v[56:57]
	v_pk_fma_f32 v[10:11], v[70:71], v[14:15], v[10:11]
	v_pk_fma_f32 v[54:55], v[72:73], v[24:25], v[54:55]
	v_pk_fma_f32 v[56:57], v[6:7], v[18:19], v[56:57]
	v_pk_fma_f32 v[12:13], v[72:73], v[16:17], v[12:13]
	v_pk_fma_f32 v[6:7], v[6:7], v[22:23], v[10:11]
	v_pk_fma_f32 v[54:55], v[8:9], v[20:21], v[54:55]
	v_pk_fma_f32 v[8:9], v[8:9], v[24:25], v[12:13]
	v_pk_fma_f32 v[2:3], v[2:3], v[18:19], v[6:7]
	v_pk_fma_f32 v[4:5], v[4:5], v[20:21], v[8:9]
	v_mul_f32_e32 v6, 0xbfb8aa3b, v2
	v_mul_f32_e32 v7, 0xbfb8aa3b, v3
	v_exp_f32_e32 v6, v6
	v_exp_f32_e32 v7, v7
	v_mul_f32_e32 v8, 0xbfb8aa3b, v4
	v_mul_f32_e32 v9, 0xbfb8aa3b, v5
	v_exp_f32_e32 v8, v8
	v_exp_f32_e32 v9, v9
	v_add_f32_e32 v6, 1.0, v6
	v_add_f32_e32 v7, 1.0, v7
	v_rcp_f32_e32 v6, v6
	v_rcp_f32_e32 v7, v7
	v_add_f32_e32 v8, 1.0, v8
	v_add_f32_e32 v9, 1.0, v9
	v_rcp_f32_e32 v8, v8
	v_rcp_f32_e32 v9, v9
	v_pk_mul_f32 v[2:3], v[2:3], v[6:7]
	v_mul_f32_e32 v58, 0xbfb8aa3b, v56
	v_mul_f32_e32 v59, 0xbfb8aa3b, v57
	v_mul_f32_e32 v60, 0xbfb8aa3b, v54
	v_mul_f32_e32 v61, 0xbfb8aa3b, v55
	v_pk_mul_f32 v[4:5], v[4:5], v[8:9]
	v_pk_mul_f32 v[8:9], v[68:69], v[2:3]
	v_ashrrev_i32_e32 v2, 6, v170
	v_exp_f32_e32 v58, v58
	v_exp_f32_e32 v59, v59
	v_exp_f32_e32 v60, v60
	v_exp_f32_e32 v61, v61
	v_ashrrev_i32_e32 v3, 31, v2
	v_lshlrev_b64 v[10:11], 15, v[2:3]
	v_and_b32_e32 v12, 0x80, v0
	v_lshlrev_b32_e32 v12, 6, v12
	v_and_b32_e32 v248, 0x78, v0
	v_lshl_or_b32 v12, v248, 2, v12
	v_and_b32_e32 v14, 56, v170
	v_lshl_add_u64 v[10:11], s[10:11], 0, v[10:11]
	v_ashrrev_i32_e32 v13, 31, v12
	v_lshl_add_u64 v[10:11], v[12:13], 1, v[10:11]
	v_and_b32_e32 v248, 32, v14
	v_lshlrev_b32_e32 v248, 5, v248
	v_and_b32_e32 v0, 24, v14
	v_lshl_or_b32 v0, v0, 1, v248
	v_mov_b32_e32 v250, 0x1000
	v_mov_b32_e32 v251, 0
	v_add_f32_e32 v134, 1.0, v134
	v_add_f32_e32 v135, 1.0, v135
	v_add_f32_e32 v136, 1.0, v136
	v_add_f32_e32 v137, 1.0, v137
	v_add_f32_e32 v58, 1.0, v58
	v_add_f32_e32 v59, 1.0, v59
	v_add_f32_e32 v60, 1.0, v60
	v_add_f32_e32 v61, 1.0, v61
	v_pk_mul_f32 v[6:7], v[66:67], v[4:5]
	v_cvt_pk_bf16_f32 v2, v104, v105
	v_cvt_pk_bf16_f32 v3, v102, v103
	v_cvt_pk_bf16_f32 v4, v44, v45
	v_cvt_pk_bf16_f32 v5, v42, v43
	v_lshl_add_u64 v[10:11], v[10:11], 0, v[0:1]
	v_rcp_f32_e32 v134, v134
	v_rcp_f32_e32 v135, v135
	v_rcp_f32_e32 v136, v136
	v_rcp_f32_e32 v137, v137
	v_rcp_f32_e32 v58, v58
	v_rcp_f32_e32 v59, v59
	v_rcp_f32_e32 v60, v60
	v_rcp_f32_e32 v61, v61
	global_store_dwordx4 v[10:11], v[2:5], off
	v_pk_mul_f32 v[126:127], v[174:175], v[126:127]
	v_pk_mul_f32 v[128:129], v[172:173], v[128:129]
	v_cvt_pk_bf16_f32 v2, v112, v113
	v_cvt_pk_bf16_f32 v3, v110, v111
	v_cvt_pk_bf16_f32 v4, v34, v35
	v_cvt_pk_bf16_f32 v5, v36, v37
	global_store_dwordx4 v[10:11], v[2:5], off offset:2048
	v_pk_mul_f32 v[130:131], v[130:131], v[136:137]
	v_pk_mul_f32 v[132:133], v[132:133], v[134:135]
	v_cvt_pk_bf16_f32 v2, v116, v117
	v_cvt_pk_bf16_f32 v3, v114, v115
	v_cvt_pk_bf16_f32 v4, v32, v33
	v_cvt_pk_bf16_f32 v5, v30, v31
	v_lshl_add_u64 v[10:11], v[10:11], 0, v[250:251]
	global_store_dwordx4 v[10:11], v[2:5], off
	v_pk_mul_f32 v[50:51], v[84:85], v[50:51]
	v_pk_mul_f32 v[52:53], v[82:83], v[52:53]
	v_cvt_pk_bf16_f32 v2, v120, v121
	v_cvt_pk_bf16_f32 v3, v118, v119
	v_cvt_pk_bf16_f32 v4, v28, v29
	v_cvt_pk_bf16_f32 v5, v26, v27
	global_store_dwordx4 v[10:11], v[2:5], off offset:2048
	v_pk_mul_f32 v[54:55], v[54:55], v[60:61]
	v_pk_mul_f32 v[56:57], v[56:57], v[58:59]
	v_cvt_pk_bf16_f32 v2, v124, v125
	v_cvt_pk_bf16_f32 v3, v122, v123
	v_cvt_pk_bf16_f32 v4, v48, v49
	v_cvt_pk_bf16_f32 v5, v46, v47
	v_lshl_add_u64 v[10:11], v[10:11], 0, v[250:251]
	global_store_dwordx4 v[10:11], v[2:5], off
	v_pk_mul_f32 v[130:131], v[142:143], v[130:131]
	v_pk_mul_f32 v[132:133], v[144:145], v[132:133]
	v_cvt_pk_bf16_f32 v2, v128, v129
	v_cvt_pk_bf16_f32 v3, v126, v127
	v_cvt_pk_bf16_f32 v4, v52, v53
	v_cvt_pk_bf16_f32 v5, v50, v51
	v_pk_mul_f32 v[54:55], v[74:75], v[54:55]
	v_pk_mul_f32 v[56:57], v[76:77], v[56:57]
	global_store_dwordx4 v[10:11], v[2:5], off offset:2048
	s_mov_b64 s[10:11], -1
	s_nop 0
	v_cvt_pk_bf16_f32 v2, v132, v133
	v_cvt_pk_bf16_f32 v3, v130, v131
	v_cvt_pk_bf16_f32 v4, v56, v57
	v_cvt_pk_bf16_f32 v5, v54, v55
	v_lshl_add_u64 v[10:11], v[10:11], 0, v[250:251]
	global_store_dwordx4 v[10:11], v[2:5], off
	s_nop 1
	v_cvt_pk_bf16_f32 v2, v40, v41
	v_cvt_pk_bf16_f32 v3, v38, v39
	v_cvt_pk_bf16_f32 v4, v8, v9
	v_cvt_pk_bf16_f32 v5, v6, v7
	global_store_dwordx4 v[10:11], v[2:5], off offset:2048
	s_cbranch_vccnz .LBB0_1252
; __device__ __forceinline__ int lane_id_opaque() { int l; asm volatile("v_mbcnt_lo_u32_b32 %0, -1, 0\n\tv_mbcnt_hi_u32_b32 %0, -1, %0" : "=v"(l)); return l; }
; #define PG8_BAR __builtin_amdgcn_s_barrier()
;     ...
;         if constexpr (ALIGN_EPI) { if (wr == 0) PG8_BAR; }
;         { const int l2 = lane_id_opaque(); E(acc, cur, ui, wr, wc, l2 & 15, l2 >> 4); }
;         S.done(cur);
;         if (!has_next) break;
; #pragma unroll
;         for (int a = 0; a < 2; ++a)
; #pragma unroll
;             for (int b = 0; b < 2; ++b)
; #pragma unroll
;                 for (int m = 0; m < 4; ++m)
; #pragma unroll
;                     for (int n = 0; n < 2; ++n) acc[a][b][m][n] = (f32x4){0.f, 0.f, 0.f, 0.f};
;         cur = nxt; cA = nA; cB = nB; ++ui;
;         if constexpr (ALIGN_EPI) { if (wr == 1) PG8_BAR; }
;     }
	s_andn2_b64 vcc, exec, s[12:13]
	s_cbranch_vccnz .LBB0_1251
	s_barrier
	s_branch .LBB0_1251

; __device__ __forceinline__ unsigned cvt_pk_bf16(float lo, float hi) { unsigned r; asm volatile("v_cvt_pk_bf16_f32 %0, %1, %2" : "=v"(r) : "v"(lo), "v"(hi)); return r; }
; __device__ __forceinline__ f32x4 silu4(const f32x4 p) { f32x4 r; r.x = siluf(p.x); r.y = siluf(p.y); r.z = siluf(p.z); r.w = siluf(p.w); return r; }
; __global__ void __launch_bounds__(NTHR, 2) mk_fwd(MKArgs args) {
;     ...
;             for (int it = byg ? (cid >> 3) * NTHR + tid : cid * NTHR + tid; it < (byg ? 16 : 128) * (DFF / 4); it += (byg ? 32 : G) * NTHR) {
;                 const int kb = (byg ? 16 * (cid & 7) : 0) + it / (DFF / 4), j = (it % (DFF / 4)) * 4; if ((kb & 31) == 0) continue;
;                 const f32x4 am2 = *(const f32x4*)(HA + ((size_t)(kb - 1) * 4 + 2) * DFF + j), am1 = *(const f32x4*)(HA + ((size_t)(kb - 1) * 4 + 3) * DFF + j);
;                 const f32x4 a0 = *(const f32x4*)(HA + ((size_t)kb * 4 + 0) * DFF + j), a1 = *(const f32x4*)(HA + ((size_t)kb * 4 + 1) * DFF + j);
;                 const f32x4 v0 = *(const f32x4*)(HV + ((size_t)kb * 2 + 0) * DFF + j), v1 = *(const f32x4*)(HV + ((size_t)kb * 2 + 1) * DFF + j);
;                 const f32x4 cbv = *(const f32x4*)(cb + j), w0 = *(const f32x4*)(cw + j), w1 = *(const f32x4*)(cw + DFF + j), w2 = *(const f32x4*)(cw + 2 * DFF + j);
;                 const f32x4 c0 = cbv + w0 * am2 + w1 * am1 + w2 * a0, c1 = cbv + w0 * am1 + w1 * a0 + w2 * a1;
;                 const f32x4 o0 = silu4(c0) * v0, o1 = silu4(c1) * v1;
;                 u32x2 p0, p1; p0.x = cvt_pk_bf16(o0.x, o0.y); p0.y = cvt_pk_bf16(o0.z, o0.w); p1.x = cvt_pk_bf16(o1.x, o1.y); p1.y = cvt_pk_bf16(o1.z, o1.w);
;                 bf16_t* ap = ACT + (size_t)(kb >> 1) * (256 * DFF) + (size_t)(j >> 6) * (256 * 64) + (128 * (kb & 1)) * 64 + (j & 63);
;                 *(u32x2*)ap = p0; *(u32x2*)(ap + 64) = p1;
.LBB0_1346:
	v_mul_hi_i32 v0, v2, s55
	v_lshrrev_b32_e32 v4, 31, v0
	v_ashrrev_i32_e32 v0, 8, v0
	v_add_u32_e32 v0, v0, v4
	v_add_u32_e32 v4, s2, v0
	v_and_b32_e32 v5, 31, v4
	v_cmp_ne_u32_e32 vcc, 0, v5
	s_and_saveexec_b64 s[24:25], vcc
	s_cbranch_execz .LBB0_1345
	v_mul_i32_i24_e32 v5, 0x580, v0
	v_lshlrev_b32_e32 v6, 2, v5
	v_sub_u32_e32 v46, v3, v6
	v_add_u32_e32 v6, -1, v4
	v_mul_hi_i32_i24_e32 v7, 0x16000, v6
	v_mul_i32_i24_e32 v6, 0x16000, v6
	v_ashrrev_i32_e32 v47, 31, v46
	v_lshl_add_u64 v[6:7], s[12:13], 0, v[6:7]
	v_lshlrev_b64 v[38:39], 2, v[46:47]
	v_lshl_add_u64 v[6:7], v[6:7], 0, v[38:39]
	v_add_co_u32_e32 v8, vcc, 0xb000, v6
	v_mul_hi_i32_i24_e32 v15, 0x16000, v4
	s_nop 0
	v_addc_co_u32_e32 v9, vcc, 0, v7, vcc
	v_add_co_u32_e32 v10, vcc, s66, v6
	v_mul_i32_i24_e32 v14, 0x16000, v4
	v_mul_hi_i32_i24_e32 v41, 0xb000, v4
	v_mul_i32_i24_e32 v40, 0xb000, v4
	v_addc_co_u32_e32 v11, vcc, 0, v7, vcc
	v_lshl_add_u64 v[14:15], s[12:13], 0, v[14:15]
	v_lshl_add_u64 v[18:19], s[10:11], 0, v[38:39]
	v_lshl_add_u64 v[22:23], s[8:9], 0, v[38:39]
	v_lshl_add_u64 v[40:41], s[14:15], 0, v[40:41]
	global_load_dwordx4 v[6:9], v[8:9], off
	s_nop 0
	global_load_dwordx4 v[10:13], v[10:11], off offset:2048
	v_lshl_add_u64 v[34:35], v[14:15], 0, v[38:39]
	global_load_dwordx4 v[18:21], v[18:19], off
	v_lshl_add_u64 v[26:27], s[18:19], 0, v[38:39]
	global_load_dwordx4 v[22:25], v[22:23], off
	v_lshl_add_u64 v[42:43], v[40:41], 0, v[38:39]
	global_load_dwordx4 v[14:17], v[34:35], off
	v_lshl_add_u64 v[30:31], s[20:21], 0, v[38:39]
	global_load_dwordx4 v[26:29], v[26:27], off
	v_sub_u32_e32 v47, v2, v5
	global_load_dwordx4 v[38:41], v[42:43], off
	v_add_co_u32_e32 v34, vcc, s82, v34
	global_load_dwordx4 v[30:33], v[30:31], off
	s_nop 0
	v_addc_co_u32_e32 v35, vcc, 0, v35, vcc
	global_load_dwordx4 v[34:37], v[34:35], off offset:2048
	v_add_co_u32_e32 v42, vcc, s82, v42
	v_lshrrev_b32_e32 v4, 1, v4
	s_nop 0
	v_addc_co_u32_e32 v43, vcc, 0, v43, vcc
	global_load_dwordx4 v[42:45], v[42:43], off offset:2048
	v_lshlrev_b32_e32 v0, 14, v0
	v_and_b32_e32 v0, 0x4000, v0
	s_waitcnt vmcnt(6)
	v_pk_fma_f32 v[6:7], v[6:7], v[22:23], v[18:19]
	v_pk_fma_f32 v[8:9], v[8:9], v[24:25], v[20:21]
	s_waitcnt vmcnt(4)
	v_pk_fma_f32 v[6:7], v[10:11], v[26:27], v[6:7]
	v_pk_fma_f32 v[10:11], v[10:11], v[22:23], v[18:19]
	v_pk_fma_f32 v[8:9], v[12:13], v[28:29], v[8:9]
	v_pk_fma_f32 v[12:13], v[12:13], v[24:25], v[20:21]
	v_pk_fma_f32 v[10:11], v[14:15], v[26:27], v[10:11]
	s_waitcnt vmcnt(2)
	v_pk_fma_f32 v[6:7], v[14:15], v[30:31], v[6:7]
	v_pk_fma_f32 v[8:9], v[16:17], v[32:33], v[8:9]
	v_pk_fma_f32 v[12:13], v[16:17], v[28:29], v[12:13]
	s_waitcnt vmcnt(1)
	v_pk_fma_f32 v[10:11], v[34:35], v[30:31], v[10:11]
	v_mul_f32_e32 v5, 0xbfb8aa3b, v6
	v_pk_fma_f32 v[12:13], v[36:37], v[32:33], v[12:13]
	v_mul_f32_e32 v14, 0xbfb8aa3b, v7
	v_mul_f32_e32 v15, 0xbfb8aa3b, v8
	v_mul_f32_e32 v16, 0xbfb8aa3b, v9
	v_exp_f32_e32 v5, v5
	v_mul_f32_e32 v17, 0xbfb8aa3b, v10
	v_mul_f32_e32 v18, 0xbfb8aa3b, v11
	v_exp_f32_e32 v14, v14
	v_exp_f32_e32 v15, v15
	v_exp_f32_e32 v16, v16
	v_mul_f32_e32 v19, 0xbfb8aa3b, v12
	v_exp_f32_e32 v21, v17
	v_exp_f32_e32 v18, v18
	v_exp_f32_e32 v19, v19
	v_add_f32_e32 v5, 1.0, v5
	v_add_f32_e32 v17, 1.0, v14
	v_add_f32_e32 v22, 1.0, v15
	v_add_f32_e32 v23, 1.0, v16
	v_rcp_f32_e32 v14, v5
	v_add_f32_e32 v5, 1.0, v21
	v_add_f32_e32 v21, 1.0, v18
	v_rcp_f32_e32 v15, v17
	v_rcp_f32_e32 v16, v22
	v_rcp_f32_e32 v17, v23
	v_add_f32_e32 v22, 1.0, v19
	v_rcp_f32_e32 v18, v5
	v_rcp_f32_e32 v19, v21
	v_mul_f32_e32 v20, 0xbfb8aa3b, v13
	v_exp_f32_e32 v20, v20
	v_pk_mul_f32 v[8:9], v[8:9], v[16:17]
	v_pk_mul_f32 v[6:7], v[6:7], v[14:15]
	v_pk_mul_f32 v[10:11], v[10:11], v[18:19]
	v_pk_mul_f32 v[8:9], v[40:41], v[8:9]
	v_pk_mul_f32 v[6:7], v[38:39], v[6:7]
	s_waitcnt vmcnt(0)
	v_pk_mul_f32 v[10:11], v[42:43], v[10:11]
	v_cvt_pk_bf16_f32 v6, v6, v7
	v_cvt_pk_bf16_f32 v7, v8, v9
	v_add_f32_e32 v23, 1.0, v20
	v_cvt_pk_bf16_f32 v8, v10, v11
	v_ashrrev_i32_e32 v10, 4, v47
	v_mul_hi_i32_i24_e32 v5, 0x2c0000, v4
	v_mul_i32_i24_e32 v4, 0x2c0000, v4
	v_ashrrev_i32_e32 v11, 31, v10
	v_rcp_f32_e32 v20, v22
	v_rcp_f32_e32 v21, v23
	v_lshl_add_u64 v[4:5], s[16:17], 0, v[4:5]
	v_lshlrev_b64 v[10:11], 15, v[10:11]
	v_lshl_add_u64 v[4:5], v[4:5], 0, v[10:11]
	v_lshl_add_u64 v[4:5], v[4:5], 0, v[0:1]
	v_and_b32_e32 v0, 28, v46
	v_lshlrev_b32_e32 v0, 1, v0
	v_and_b32_e32 v248, 32, v46
	v_lshl_or_b32 v0, v248, 5, v0
	v_pk_mul_f32 v[12:13], v[12:13], v[20:21]
	v_lshl_add_u64 v[4:5], v[4:5], 0, v[0:1]
	v_pk_mul_f32 v[12:13], v[44:45], v[12:13]
	s_nop 0
	v_cvt_pk_bf16_f32 v9, v12, v13
	global_store_dwordx2 v[4:5], v[6:7], off
	global_store_dwordx2 v[4:5], v[8:9], off offset:2048
	s_branch .LBB0_1345

; #define PG8_STAGE(bufoff, gbase, voff) do { _Pragma("unroll") for (int _i = 0; _i < 2; ++_i) \
;         __builtin_amdgcn_global_load_lds((const unsigned*)((const char*)(gbase) + (voff)[_i]), (PG8_LAS unsigned*)(lds + (bufoff) + ldsw + _i * 8192), 16, 0, 0); } while (0)
; #define PG8_WAIT_V(n) asm volatile("s_waitcnt vmcnt(" #n ")" ::: "memory")
; #define PG8_BAR __builtin_amdgcn_s_barrier()
;     __device__ __forceinline__ size_t b_off(const pg8::Unit& u) const { return (size_t)(u.pm >> 3) * 4 * 131072; }
;     ...
;     for (int i = 0; i < 2; ++i) { int R, C; stage_rc(tid * 16 + i * 8192, R, C); const int Rb = Epi::PERM ? ((R & ~31) + perm32(R & 31)) : R;
;         const int Ra = ROWP ? (128 * (R >> 6) + 8 * (R & 15) + ((R >> 4) & 3)) : R;
;         voffA[i] = (unsigned)(Ra * LDA + C) * 2u; voffB[i] = (unsigned)(Rb * LDB + C) * 2u; }
;     ...
;     const char* cA = (const char*)g.A + (size_t)cur.pm * tstepA + (size_t)cur.pn * APN + kofA; const char* cB = (const char*)g.Bt + (size_t)cur.pn * tstepB + S.b_off(cur) + kofB;
;     S.a_ready(cur);
;     if constexpr (SP2) {
;         PG8_STAGE(PG8_SB(0, 0), cB, voffB); PG8_STAGE(PG8_SB(0, 1), cB + hstepB, voffB); PG8_STAGE(PG8_SA(0, 0), cA, voffA); PG8_STAGE(PG8_SA(0, 1), cA + hstepA, voffA);
;         P();
;         if (wr == 1) PG8_BAR;
;         PG8_WAIT_V(2); PG8_BAR;
;         PG8_STAGE(PG8_SB(1, 0), cB + kstep, voffB); PG8_STAGE(PG8_SA(1, 0), cA + kstepA, voffA); PG8_STAGE(PG8_SB(1, 1), cB + hstepB + kstep, voffB);
;         PG8_WAIT_V(6); PG8_BAR;
.LBB0_1428:
	s_waitcnt vmcnt(0)
	v_bfe_i32 v4, v0, 27, 1
	s_waitcnt lgkmcnt(0)
	v_lshlrev_b32_e32 v2, 4, v0
	v_lshrrev_b32_e32 v4, 22, v4
	v_add_u32_e32 v4, v2, v4
	v_and_b32_e32 v4, 0xfffffc00, v4
	v_sub_u32_e32 v4, v2, v4
	v_ashrrev_i32_e32 v3, 31, v0
	v_lshrrev_b32_e32 v5, 4, v4
	s_add_u32 s6, s76, s6
	v_lshrrev_b32_e32 v3, 26, v3
	v_bitop3_b32 v4, v5, v4, 32 bitop3:0x6c
	s_addc_u32 s7, s77, s7
	v_add_u32_e32 v3, v0, v3
	v_ashrrev_i32_e32 v6, 31, v4
	s_add_u32 s33, s6, 0x24104000
	v_ashrrev_i32_e32 v3, 6, v3
	v_lshrrev_b32_e32 v6, 26, v6
	s_addc_u32 s36, s7, 0
	s_mul_i32 s9, s48, 0x1600000
	v_lshlrev_b32_e32 v5, 3, v3
	v_add_u32_e32 v6, v4, v6
	s_mul_hi_u32 s8, s48, 0x1600000
	s_add_u32 s9, s6, s9
	v_and_b32_e32 v5, -16, v5
	v_ashrrev_i32_e32 v7, 6, v6
	v_and_b32_e32 v6, 0xc0, v6
	s_addc_u32 s8, s7, s8
	v_add_u32_e32 v5, v7, v5
	v_sub_u32_e32 v4, v4, v6
	s_add_u32 s37, s9, 0x12704000
	v_lshlrev_b32_e32 v3, 5, v3
	v_ashrrev_i16_sdwa v4, v241, sext(v4) dst_sel:DWORD dst_unused:UNUSED_PAD src0_sel:DWORD src1_sel:BYTE_0
	v_lshlrev_b32_e32 v6, 1, v5
	v_lshrrev_b32_e32 v8, 2, v5
	v_and_b32_e32 v7, 3, v7
	s_mov_b32 s9, 0x1ffffe0
	v_and_b32_e32 v3, 32, v3
	v_bfe_i32 v4, v4, 0, 16
	v_and_b32_e32 v6, 24, v6
	v_and_b32_e32 v8, 4, v8
	v_and_or_b32 v7, v5, s9, v7
	v_or3_b32 v6, v7, v8, v6
	v_add_lshl_u32 v3, v3, v4, 1
	v_add_u32_e32 v2, 0x2000, v2
	v_lshl_add_u32 v194, v5, 7, v3
	v_and_b32_e32 v248, 0x380, v194
	v_lshlrev_b32_e32 v248, 4, v248
	v_and_b32_e32 v249, 0x3c00, v194
	v_lshrrev_b32_e32 v249, 4, v249
	v_and_b32_e32 v250, 0x40, v194
	v_lshlrev_b32_e32 v250, 4, v250
	v_and_b32_e32 v251, 0x30, v194
	v_or3_b32 v194, v248, v249, v250
	v_or_b32_e32 v194, v194, v251
	v_lshl_add_u32 v196, v6, 7, v3
	v_ashrrev_i32_e32 v3, 31, v2
	v_lshrrev_b32_e32 v3, 22, v3
	v_add_u32_e32 v3, v2, v3
	v_ashrrev_i32_e32 v3, 10, v3
	v_mul_i32_i24_e32 v4, 0x400, v3
	v_sub_u32_e32 v2, v2, v4
	v_lshrrev_b32_e32 v4, 4, v2
	v_bitop3_b32 v2, v4, v2, 32 bitop3:0x6c
	v_ashrrev_i32_e32 v5, 31, v2
	v_lshrrev_b32_e32 v5, 26, v5
	v_lshlrev_b32_e32 v4, 3, v3
	v_add_u32_e32 v5, v2, v5
	v_and_b32_e32 v4, -16, v4
	v_ashrrev_i32_e32 v6, 6, v5
	s_addc_u32 s40, s8, 0
	s_ashr_i32 s8, s22, 6
	v_add_u32_e32 v4, v6, v4
	v_and_b32_e32 v6, 3, v6
	v_and_or_b32 v6, v4, s9, v6
	s_ashr_i32 s26, s22, 8
	s_lshl_b32 s41, s8, 10
	s_mul_i32 s9, s86, 0x2c0000
	s_mul_hi_i32 s10, s86, 0x2c0000
	s_add_u32 s9, s37, s9
	s_addc_u32 s23, s40, s10
	s_add_u32 s10, s9, 0x2b8000
	v_and_b32_e32 v5, 0xc0, v5
	s_addc_u32 s11, s23, 0
	s_add_i32 s46, s41, 0
	v_sub_u32_e32 v2, v2, v5
	s_add_i32 m0, s46, 0x10000
	v_lshlrev_b32_e32 v3, 5, v3
	v_ashrrev_i16_sdwa v2, v241, sext(v2) dst_sel:DWORD dst_unused:UNUSED_PAD src0_sel:DWORD src1_sel:BYTE_0
	v_lshlrev_b32_e32 v5, 1, v4
	v_lshrrev_b32_e32 v7, 2, v4
	s_mul_i32 s13, s87, 0x2c0000
	global_load_lds_dwordx4 v196, s[10:11]
	s_add_i32 m0, s46, 0x12000
	v_and_b32_e32 v3, 32, v3
	v_bfe_i32 v2, v2, 0, 16
	v_and_b32_e32 v5, 24, v5
	v_and_b32_e32 v7, 4, v7
	s_mul_hi_i32 s12, s87, 0x2c0000
	s_add_u32 s24, s33, s13
	v_or3_b32 v5, v6, v7, v5
	v_add_lshl_u32 v2, v3, v2, 1
	s_addc_u32 s25, s36, s12
	v_lshl_add_u32 v200, v5, 7, v2
	s_add_u32 s12, s9, 0x2bc000
	global_load_lds_dwordx4 v200, s[10:11]
	s_addc_u32 s13, s23, 0
	s_add_i32 m0, s46, 0x14000
	s_mov_b32 s96, s48
	global_load_lds_dwordx4 v196, s[12:13]
	s_add_i32 m0, s46, 0x16000
	s_add_u32 s28, s24, 0x2b8000
	s_addc_u32 s29, s25, 0
	s_add_i32 s47, s46, 0x2000
	global_load_lds_dwordx4 v200, s[12:13]
	s_mov_b32 m0, s46
	s_add_u32 s12, s24, 0x2bc000
	v_lshl_add_u32 v198, v4, 7, v2
	v_and_b32_e32 v248, 0x380, v198
	v_lshlrev_b32_e32 v248, 4, v248
	v_and_b32_e32 v249, 0x3c00, v198
	v_lshrrev_b32_e32 v249, 4, v249
	v_and_b32_e32 v250, 0x40, v198
	v_lshlrev_b32_e32 v250, 4, v250
	v_and_b32_e32 v251, 0x30, v198
	v_or3_b32 v198, v248, v249, v250
	v_or_b32_e32 v198, v198, v251
	global_load_lds_dwordx4 v194, s[28:29]
	s_mov_b32 m0, s47
	s_addc_u32 s13, s25, 0
	s_add_i32 s48, s46, 0x4000
	global_load_lds_dwordx4 v198, s[28:29]
	s_mov_b32 m0, s48
	s_add_i32 s49, s46, 0x6000
	global_load_lds_dwordx4 v194, s[12:13]
	s_mov_b32 m0, s49
	s_cmp_eq_u32 s26, 1
	global_load_lds_dwordx4 v198, s[12:13]
	s_mov_b32 s91, s63
	s_cselect_b64 s[12:13], -1, 0
	s_cmp_lg_u32 s26, 1
	s_cbranch_scc1 .LBB0_1430
	s_barrier
